# grid barrier: all workgroups poll the top-level generation word directly (drops the per-XCD generation hop); first-barrier census loads batched
# speedup vs baseline: 1.0046x; 1.0017x over previous
; __device__ __forceinline__ unsigned xb_ld(unsigned* p)              { return __hip_atomic_load(p, __ATOMIC_RELAXED, __HIP_MEMORY_SCOPE_AGENT); }
; __device__ __forceinline__ void xcd_barrier_complete(unsigned* bar, unsigned x, unsigned& nloc, unsigned& nx) {
;     const unsigned G = gridDim.x;
;     unsigned sum, cnt, mine, sp = 0u;
;     for (;;) {
;         sum = 0u; cnt = 0u; mine = 0u;
; #pragma unroll
;         for (unsigned j = 0; j < 16; ++j) { const unsigned c = xb_ld(&bar[XB_XCNT(j)]); sum += c; cnt += (c > 0u) ? 1u : 0u; mine = (j == x) ? c : mine; }
;         if (sum == G) break;
;         __builtin_amdgcn_s_sleep(1);
;         if ((++sp & 255u) == 0u) { if (xb_ld(&bar[XB_TMO])) break; if (sp > XB_SPIN_CAP) { atomicAdd(&bar[XB_TMO], 1u); break; } }
;     }
;     nloc = mine > 0u ? mine : 1u; nx = cnt > 0u ? cnt : 1u;
; }
.LBB0_858:
	v_readlane_b32 s0, v254, 10
	v_readlane_b32 s1, v254, 11
	s_mov_b64 s[4:5], -1
	s_nop 4
	global_load_dword v1, v0, s[0:1] sc1
	v_readlane_b32 s0, v254, 12
	v_readlane_b32 s1, v254, 13
	s_waitcnt lgkmcnt(0)
	s_nop 4
	global_load_dword v2, v0, s[0:1] sc1
	v_readlane_b32 s0, v254, 14
	v_readlane_b32 s1, v254, 15
	s_nop 4
	global_load_dword v3, v0, s[0:1] sc1
	v_readlane_b32 s0, v254, 16
	v_readlane_b32 s1, v254, 17
	s_nop 4
	global_load_dword v4, v0, s[0:1] sc1
	v_readlane_b32 s0, v254, 18
	v_readlane_b32 s1, v254, 19
	s_nop 4
	global_load_dword v5, v0, s[0:1] sc1
	v_readlane_b32 s0, v254, 20
	v_readlane_b32 s1, v254, 21
	s_nop 4
	global_load_dword v6, v0, s[0:1] sc1
	v_readlane_b32 s0, v254, 22
	v_readlane_b32 s1, v254, 23
	s_nop 4
	global_load_dword v7, v0, s[0:1] sc1
	v_readlane_b32 s0, v254, 24
	v_readlane_b32 s1, v254, 25
	s_nop 4
	global_load_dword v8, v0, s[0:1] sc1
	v_readlane_b32 s0, v254, 26
	v_readlane_b32 s1, v254, 27
	s_nop 4
	global_load_dword v9, v0, s[0:1] sc1
	v_readlane_b32 s0, v254, 28
	v_readlane_b32 s1, v254, 29
	s_nop 4
	global_load_dword v10, v0, s[0:1] sc1
	v_readlane_b32 s0, v254, 30
	v_readlane_b32 s1, v254, 31
	s_nop 4
	global_load_dword v11, v0, s[0:1] sc1
	v_readlane_b32 s0, v254, 32
	v_readlane_b32 s1, v254, 33
	s_nop 4
	global_load_dword v12, v0, s[0:1] sc1
	v_readlane_b32 s0, v254, 34
	v_readlane_b32 s1, v254, 35
	s_nop 4
	global_load_dword v13, v0, s[0:1] sc1
	v_readlane_b32 s0, v254, 36
	v_readlane_b32 s1, v254, 37
	s_nop 4
	global_load_dword v14, v0, s[0:1] sc1
	v_readlane_b32 s0, v254, 38
	v_readlane_b32 s1, v254, 39
	s_nop 4
	global_load_dword v15, v0, s[0:1] sc1
	v_readlane_b32 s0, v254, 40
	v_readlane_b32 s1, v254, 41
	s_nop 4
	global_load_dword v16, v0, s[0:1] sc1
	s_mov_b64 s[0:1], -1
	s_waitcnt vmcnt(0)
	v_add_u32_e32 v17, v2, v1
	v_add_u32_e32 v17, v17, v3
	v_add_u32_e32 v17, v17, v4
	v_add_u32_e32 v17, v17, v5
	v_add_u32_e32 v17, v17, v6
	v_add_u32_e32 v17, v17, v7
	v_add_u32_e32 v17, v17, v8
	v_add_u32_e32 v17, v17, v9
	v_add_u32_e32 v17, v17, v10
	v_add_u32_e32 v17, v17, v11
	v_add_u32_e32 v17, v17, v12
	v_add_u32_e32 v17, v17, v13
	v_add_u32_e32 v17, v17, v14
	v_add_u32_e32 v17, v17, v15
	v_add_u32_e32 v17, v17, v16
	v_cmp_eq_u32_e32 vcc, s94, v17
	s_cbranch_vccnz .LBB0_857
	s_and_b32 s0, s9, 0xff
	s_cmp_eq_u32 s0, 0
	s_mov_b64 s[0:1], -1
	s_mov_b64 s[6:7], -1
	s_sleep 1
	s_cbranch_scc1 .LBB0_862
	s_and_b64 vcc, exec, s[6:7]
	s_cbranch_vccz .LBB0_857

; __device__ __forceinline__ unsigned xb_ld(unsigned* p)              { return __hip_atomic_load(p, __ATOMIC_RELAXED, __HIP_MEMORY_SCOPE_AGENT); }
; __device__ __forceinline__ unsigned xb_add(unsigned* p, unsigned v) { return __hip_atomic_fetch_add(p, v, __ATOMIC_RELAXED, __HIP_MEMORY_SCOPE_AGENT); }
; #define XB_SPIN(cond, bar) do { unsigned _sp = 0; while (cond) { __builtin_amdgcn_s_sleep(1); \
;     if ((++_sp & 255u) == 0u) { if (xb_ld(&(bar)[XB_TMO])) break; if (_sp > XB_SPIN_CAP) { atomicAdd(&(bar)[XB_TMO], 1u); break; } } } } while (0)
; __device__ __forceinline__ void xcd_barrier(unsigned* bar, volatile LAS unsigned* st) {
;     ...
;         const unsigned old = xb_add(&bar[XB_XSUB(x)], 1u);
;         const unsigned gen = old / nloc;
;         if (old + 1u == (gen + 1u) * nloc) {
;             __builtin_amdgcn_fence(__ATOMIC_RELEASE, "agent");
;             asm volatile("s_waitcnt vmcnt(0)" ::: "memory");
;             const unsigned og = xb_add(&bar[XB_TOP], 1u);
;             const unsigned tg = og / nx;
;             if (og + 1u == (tg + 1u) * nx) xb_add(&bar[XB_TOPGEN], 1u);
;             else XB_SPIN(xb_ld(&bar[XB_TOPGEN]) == tg, bar);
;             __builtin_amdgcn_fence(__ATOMIC_ACQUIRE, "agent");
;             xb_add(&bar[XB_XGEN(x)], 1u);
;             asm volatile("s_waitcnt vmcnt(0)" ::: "memory");
;         } else {
;             XB_SPIN(xb_ld(&bar[XB_XGEN(x)]) == gen, bar);
.LBB0_872:
	s_or_b64 exec, exec, s[6:7]
	v_cvt_f32_u32_e32 v5, v3
	s_waitcnt vmcnt(0)
	v_readfirstlane_b32 s0, v4
	v_sub_u32_e32 v4, 0, v3
	v_rcp_iflag_f32_e32 v5, v5
	v_add_u32_e32 v6, s0, v1
	v_mul_f32_e32 v5, 0x4f7ffffe, v5
	v_cvt_u32_f32_e32 v5, v5
	v_mul_lo_u32 v1, v4, v5
	v_mul_hi_u32 v1, v5, v1
	v_add_u32_e32 v1, v5, v1
	v_mul_hi_u32 v1, v6, v1
	v_mul_lo_u32 v4, v1, v3
	v_sub_u32_e32 v4, v6, v4
	v_add_u32_e32 v5, 1, v1
	v_cmp_ge_u32_e32 vcc, v4, v3
	s_nop 1
	v_cndmask_b32_e32 v1, v1, v5, vcc
	v_sub_u32_e32 v5, v4, v3
	v_cndmask_b32_e32 v4, v4, v5, vcc
	v_add_u32_e32 v5, 1, v1
	v_cmp_ge_u32_e32 vcc, v4, v3
	v_add_u32_e32 v4, 1, v6
	s_nop 0
	v_cndmask_b32_e32 v1, v1, v5, vcc
	v_mul_lo_u32 v5, v3, v1
	v_add_u32_e32 v3, v5, v3
	v_cmp_ne_u32_e32 vcc, v4, v3
	s_and_saveexec_b64 s[0:1], vcc
	s_xor_b64 s[6:7], exec, s[0:1]
	s_cbranch_execz .LBB0_886
	s_waitcnt lgkmcnt(0)
	v_readlane_b32 s8, v254, 44
	v_readlane_b32 s9, v254, 45
	s_nop 4
	global_load_dword v2, v0, s[8:9] sc1
	s_waitcnt vmcnt(0)
	v_cmp_eq_u32_e32 vcc, v2, v1
	s_and_saveexec_b64 s[0:1], vcc
	s_cbranch_execz .LBB0_885
	s_mov_b32 s20, 1
	s_mov_b64 s[10:11], 0
	s_branch .LBB0_876

; __device__ __forceinline__ unsigned xb_add(unsigned* p, unsigned v) { return __hip_atomic_fetch_add(p, v, __ATOMIC_RELAXED, __HIP_MEMORY_SCOPE_AGENT); }
; __device__ __forceinline__ void xcd_barrier(unsigned* bar, volatile LAS unsigned* st) {
;     ...
;             __builtin_amdgcn_fence(__ATOMIC_ACQUIRE, "agent");
;             xb_add(&bar[XB_XGEN(x)], 1u);
;             asm volatile("s_waitcnt vmcnt(0)" ::: "memory");
.LBB0_903:
	s_or_b64 exec, exec, s[0:1]
	s_mov_b64 s[0:1], exec
	v_mbcnt_lo_u32_b32 v1, s0, 0
	v_mbcnt_hi_u32_b32 v1, s1, v1
	v_cmp_eq_u32_e32 vcc, 0, v1
	s_waitcnt vmcnt(0)
	buffer_inv sc1
	s_and_saveexec_b64 s[6:7], vcc
	s_cbranch_execz .LBB0_905
	s_bcnt1_i32_b64 s0, s[0:1]
.LBB0_905:
	s_or_b64 exec, exec, s[6:7]
	s_waitcnt vmcnt(0)
